# v18 + P6 FFN-up epilogue rewritten by hand on packed f32 math (conv as 3 pk_fma per column pair, gelu on pairs, neighbours by 2 DPP moves, edge partials as one dwordx4): 789 instr vs ~1650
# speedup vs baseline: 1.0103x; 1.0103x over previous
;     __device__ __forceinline__ void operator()(pg8::f32x4 (&acc)[2][2][4][2], const pg8::Unit& u, int wr_, int wc_, int fr_, int fq_) const {
;         int t_ = tid_from(wr_ * 4 + wc_); asm volatile("" : "+v"(t_));
;         const int fr = t_ & 15, fq = (t_ >> 4) & 3, wc = (t_ >> 6) & 3, wr = t_ >> 8; (void)wr_; (void)wc_; (void)fr_; (void)fq_;
;         const unsigned hc0 = (unsigned)(u.pn * 128 + wc * 32 + 8 * fq);
;         const bool e0 = fr == 0, e3 = fr == 15;
;         __builtin_amdgcn_sched_barrier(0);
; #pragma unroll
;         for (int ai = 0; ai < 2; ++ai) {
;             const int rbase = u.pm * 256 + ai * 128 + wr * 64;
;             const unsigned eb0 = (unsigned)((rbase >> 6) << 1) * (unsigned)DFF, eb3 = eb0 + (unsigned)DFF;
; #pragma unroll
;             for (int n = 0; n < 2; ++n) {
;                 const unsigned hc = hc0 + 4u * (unsigned)n;
;                 const pg8::f32x4 w0 = *(const GAS pg8::f32x4*)&cw[hc], w1 = *(const GAS pg8::f32x4*)&cw[(unsigned)DFF + hc], w2 = *(const GAS pg8::f32x4*)&cw[2u * (unsigned)DFF + hc], bb = *(const GAS pg8::f32x4*)&cb[hc];
;                 if (e0) { *(GAS pg8::f32x4*)&EG[eb0 + hc] = acc[ai][0][0][n]; *(GAS pg8::f32x4*)&EU[eb0 + hc] = acc[ai][1][0][n]; }
;                 if (e3) { *(GAS pg8::f32x4*)&EG[eb3 + hc] = acc[ai][0][3][n]; *(GAS pg8::f32x4*)&EU[eb3 + hc] = acc[ai][1][3][n]; }
; #pragma unroll
;                 for (int j = 0; j < 4; ++j) {
;                     float pr[4], nx[4], gg[4];
; #pragma unroll
;                     for (int m = 0; m < 4; ++m) { gg[m] = acc[ai][0][m][n][j]; pr[m] = dpp_ror<0x121>(gg[m]); nx[m] = dpp_ror<0x12F>(gg[m]); }
; #pragma unroll
;                     for (int m = 0; m < 4; ++m) {
;                         const float pv = fr > 0 ? pr[m] : (m > 0 ? pr[m > 0 ? m - 1 : 0] : 0.f);
;                         const float nv = fr < 15 ? nx[m] : (m < 3 ? nx[m < 3 ? m + 1 : 3] : 0.f);
;                         const float cv = w0[j] * pv + w1[j] * gg[m] + w2[j] * nv + bb[j];
;                         if (m == 0) { if (e0) EP[eb0 + hc + (unsigned)j] = cv; } if (m == 3) { if (e3) EP[eb3 + hc + (unsigned)j] = cv; }
;                         acc[ai][0][m][n][j] = gelu_tanh(cv) * acc[ai][1][m][n][j];
;                     }
;                 }
;                 asm volatile("" ::: "memory"); __builtin_amdgcn_sched_barrier(0);
;             }
.LBB0_1454:
	s_mov_b32 s92, s57
	s_mov_b32 s57, s94
	s_mov_b32 s93, s52
	v_mbcnt_lo_u32_b32 v235, -1, 0
	v_mbcnt_hi_u32_b32 v235, -1, v235
	v_mov_b32_e32 v172, 0xc0135761
	v_or_b32_e32 v235, s75, v235
	v_mov_b32_e32 v173, 0xc0135761
	v_and_b32_e32 v248, 15, v235
	v_lshrrev_b32_e32 v176, 1, v235
	v_ashrrev_i32_e32 v249, 2, v235
	v_and_b32_e32 v176, 0x78, v176
	v_and_b32_e32 v249, 0xffffffc0, v249
	v_lshl_or_b32 v176, s10, 7, v176
	v_lshl_add_u32 v249, s8, 8, v249
	v_cmp_eq_u32_e64 s[12:13], 0, v248
	v_cmp_eq_u32_e64 s[30:31], 15, v248
	v_cmp_ne_u32_e64 s[10:11], 0, v248
	v_cmp_ne_u32_e64 s[62:63], 15, v248
	v_add_u32_e32 v233, v249, v248
	v_lshrrev_b32_e32 v232, 5, v249
	s_movk_i32 s8, 0x1600
	v_mul_lo_u32 v233, v233, s8
	v_mul_lo_u32 v232, v232, s8
	v_add_u32_e32 v233, v233, v176
	v_add_u32_e32 v232, v232, v176
	v_lshlrev_b32_e32 v176, 2, v176
	v_lshlrev_b32_e32 v233, 1, v233
	v_lshlrev_b32_e32 v232, 2, v232
	v_add_u32_e32 v218, 0x5800, v176
	v_add_u32_e32 v219, 0xb000, v176
	global_load_dwordx4 v[120:123], v176, s[24:25] offset:0
	global_load_dwordx4 v[124:127], v218, s[24:25] offset:0
	global_load_dwordx4 v[128:131], v219, s[24:25] offset:0
	global_load_dwordx4 v[132:135], v176, s[26:27] offset:0
	global_load_dwordx4 v[178:181], v176, s[24:25] offset:16
	global_load_dwordx4 v[182:185], v218, s[24:25] offset:16
	global_load_dwordx4 v[186:189], v219, s[24:25] offset:16
	global_load_dwordx4 v[190:193], v176, s[26:27] offset:16
	v_mov_b32_e32 v174, 0xbdd2d3e7
	v_mov_b32_e32 v175, 0xbdd2d3e7
	v_mov_b32_e32 v210, 1.0
	v_mov_b32_e32 v211, 1.0
	s_mov_b64 s[8:9], exec
	v_mov_b32_dpp v144, v84 row_ror:15 row_mask:0xf bank_mask:0xf
	v_mov_b32_dpp v145, v85 row_ror:15 row_mask:0xf bank_mask:0xf
	v_mov_b32_dpp v146, v86 row_ror:15 row_mask:0xf bank_mask:0xf
	v_mov_b32_dpp v147, v87 row_ror:15 row_mask:0xf bank_mask:0xf
	v_mov_b32_dpp v198, v140 row_ror:1 row_mask:0xf bank_mask:0xf
	v_mov_b32_dpp v148, v80 row_ror:15 row_mask:0xf bank_mask:0xf
	v_mov_b32_dpp v199, v141 row_ror:1 row_mask:0xf bank_mask:0xf
	v_mov_b32_dpp v149, v81 row_ror:15 row_mask:0xf bank_mask:0xf
	v_mov_b32_dpp v200, v142 row_ror:1 row_mask:0xf bank_mask:0xf
	v_mov_b32_dpp v150, v82 row_ror:15 row_mask:0xf bank_mask:0xf
	v_mov_b32_dpp v201, v143 row_ror:1 row_mask:0xf bank_mask:0xf
	v_mov_b32_dpp v151, v83 row_ror:15 row_mask:0xf bank_mask:0xf
	v_mov_b32_dpp v202, v84 row_ror:1 row_mask:0xf bank_mask:0xf
	v_mov_b32_dpp v164, v136 row_ror:15 row_mask:0xf bank_mask:0xf
	v_mov_b32_dpp v203, v85 row_ror:1 row_mask:0xf bank_mask:0xf
	v_mov_b32_dpp v165, v137 row_ror:15 row_mask:0xf bank_mask:0xf
	v_mov_b32_dpp v204, v86 row_ror:1 row_mask:0xf bank_mask:0xf
	v_mov_b32_dpp v166, v138 row_ror:15 row_mask:0xf bank_mask:0xf
	v_mov_b32_dpp v205, v87 row_ror:1 row_mask:0xf bank_mask:0xf
	v_mov_b32_dpp v167, v139 row_ror:15 row_mask:0xf bank_mask:0xf
	v_mov_b32_dpp v206, v80 row_ror:1 row_mask:0xf bank_mask:0xf
	v_mov_b32_dpp v207, v81 row_ror:1 row_mask:0xf bank_mask:0xf
	v_mov_b32_dpp v208, v82 row_ror:1 row_mask:0xf bank_mask:0xf
	v_mov_b32_dpp v209, v83 row_ror:1 row_mask:0xf bank_mask:0xf
	v_mov_b32_dpp v194, v140 row_shr:1 row_mask:0xf bank_mask:0xf bound_ctrl:0
	v_mov_b32_dpp v144, v140 row_shl:1 row_mask:0xf bank_mask:0xf
	v_mov_b32_dpp v195, v141 row_shr:1 row_mask:0xf bank_mask:0xf bound_ctrl:0
	v_mov_b32_dpp v145, v141 row_shl:1 row_mask:0xf bank_mask:0xf
	v_mov_b32_dpp v196, v142 row_shr:1 row_mask:0xf bank_mask:0xf bound_ctrl:0
	v_mov_b32_dpp v146, v142 row_shl:1 row_mask:0xf bank_mask:0xf
	v_mov_b32_dpp v197, v143 row_shr:1 row_mask:0xf bank_mask:0xf bound_ctrl:0
	v_mov_b32_dpp v147, v143 row_shl:1 row_mask:0xf bank_mask:0xf
	v_mov_b32_dpp v198, v84 row_shr:1 row_mask:0xf bank_mask:0xf
	v_mov_b32_dpp v148, v84 row_shl:1 row_mask:0xf bank_mask:0xf
	v_mov_b32_dpp v199, v85 row_shr:1 row_mask:0xf bank_mask:0xf
	v_mov_b32_dpp v149, v85 row_shl:1 row_mask:0xf bank_mask:0xf
	v_mov_b32_dpp v200, v86 row_shr:1 row_mask:0xf bank_mask:0xf
	v_mov_b32_dpp v150, v86 row_shl:1 row_mask:0xf bank_mask:0xf
	v_mov_b32_dpp v201, v87 row_shr:1 row_mask:0xf bank_mask:0xf
	v_mov_b32_dpp v151, v87 row_shl:1 row_mask:0xf bank_mask:0xf
	v_mov_b32_dpp v202, v80 row_shr:1 row_mask:0xf bank_mask:0xf
	v_mov_b32_dpp v164, v80 row_shl:1 row_mask:0xf bank_mask:0xf
	v_mov_b32_dpp v203, v81 row_shr:1 row_mask:0xf bank_mask:0xf
	v_mov_b32_dpp v165, v81 row_shl:1 row_mask:0xf bank_mask:0xf
	v_mov_b32_dpp v204, v82 row_shr:1 row_mask:0xf bank_mask:0xf
	v_mov_b32_dpp v166, v82 row_shl:1 row_mask:0xf bank_mask:0xf
	v_mov_b32_dpp v205, v83 row_shr:1 row_mask:0xf bank_mask:0xf
	v_mov_b32_dpp v167, v83 row_shl:1 row_mask:0xf bank_mask:0xf
	v_mov_b32_dpp v206, v136 row_shr:1 row_mask:0xf bank_mask:0xf
	v_mov_b32_dpp v168, v136 row_shl:1 row_mask:0xf bank_mask:0xf bound_ctrl:0
	v_mov_b32_dpp v207, v137 row_shr:1 row_mask:0xf bank_mask:0xf
	v_mov_b32_dpp v169, v137 row_shl:1 row_mask:0xf bank_mask:0xf bound_ctrl:0
	v_mov_b32_dpp v208, v138 row_shr:1 row_mask:0xf bank_mask:0xf
	v_mov_b32_dpp v170, v138 row_shl:1 row_mask:0xf bank_mask:0xf bound_ctrl:0
	v_mov_b32_dpp v209, v139 row_shr:1 row_mask:0xf bank_mask:0xf
	v_mov_b32_dpp v171, v139 row_shl:1 row_mask:0xf bank_mask:0xf bound_ctrl:0
	s_waitcnt vmcnt(0)
; #define GAS __attribute__((address_space(1)))
; template <int CTRL> __device__ __forceinline__ float dpp_ror(float v) { return __builtin_bit_cast(float, __builtin_amdgcn_update_dpp(0, __builtin_bit_cast(int, v), CTRL, 0xf, 0xf, false)); }
;     __device__ __forceinline__ void operator()(pg8::f32x4 (&acc)[2][2][4][2], const pg8::Unit& u, int wr_, int wc_, int fr_, int fq_) const {
;     ...
; #pragma unroll
;             for (int n = 0; n < 2; ++n) {
;                 const unsigned hc = hc0 + 4u * (unsigned)n;
;                 const pg8::f32x4 w0 = *(const GAS pg8::f32x4*)&cw[hc], w1 = *(const GAS pg8::f32x4*)&cw[(unsigned)DFF + hc], w2 = *(const GAS pg8::f32x4*)&cw[2u * (unsigned)DFF + hc], bb = *(const GAS pg8::f32x4*)&cb[hc];
;                 if (e0) { *(GAS pg8::f32x4*)&EG[eb0 + hc] = acc[ai][0][0][n]; *(GAS pg8::f32x4*)&EU[eb0 + hc] = acc[ai][1][0][n]; }
;                 if (e3) { *(GAS pg8::f32x4*)&EG[eb3 + hc] = acc[ai][0][3][n]; *(GAS pg8::f32x4*)&EU[eb3 + hc] = acc[ai][1][3][n]; }
; #pragma unroll
;                 for (int j = 0; j < 4; ++j) {
;                     float pr[4], nx[4], gg[4];
; #pragma unroll
;                     for (int m = 0; m < 4; ++m) { gg[m] = acc[ai][0][m][n][j]; pr[m] = dpp_ror<0x121>(gg[m]); nx[m] = dpp_ror<0x12F>(gg[m]); }
; #pragma unroll
;                     for (int m = 0; m < 4; ++m) {
;                         const float pv = fr > 0 ? pr[m] : (m > 0 ? pr[m > 0 ? m - 1 : 0] : 0.f);
;                         const float nv = fr < 15 ? nx[m] : (m < 3 ? nx[m < 3 ? m + 1 : 3] : 0.f);
;                         const float cv = w0[j] * pv + w1[j] * gg[m] + w2[j] * nv + bb[j];
;                         if (m == 0) { if (e0) EP[eb0 + hc + (unsigned)j] = cv; } if (m == 3) { if (e3) EP[eb3 + hc + (unsigned)j] = cv; }
;                         acc[ai][0][m][n][j] = gelu_tanh(cv) * acc[ai][1][m][n][j];
;                     }
;                 }
;                 asm volatile("" ::: "memory"); __builtin_amdgcn_sched_barrier(0);
	v_pk_fma_f32 v[194:195], v[120:121], v[194:195], v[132:133]
	v_pk_fma_f32 v[196:197], v[122:123], v[196:197], v[134:135]
	v_pk_fma_f32 v[198:199], v[120:121], v[198:199], v[132:133]
	v_pk_fma_f32 v[200:201], v[122:123], v[200:201], v[134:135]
	v_pk_fma_f32 v[202:203], v[120:121], v[202:203], v[132:133]
	v_pk_fma_f32 v[204:205], v[122:123], v[204:205], v[134:135]
	v_pk_fma_f32 v[206:207], v[120:121], v[206:207], v[132:133]
	v_pk_fma_f32 v[208:209], v[122:123], v[208:209], v[134:135]
	v_pk_fma_f32 v[194:195], v[124:125], v[140:141], v[194:195]
	v_pk_fma_f32 v[196:197], v[126:127], v[142:143], v[196:197]
	v_pk_fma_f32 v[198:199], v[124:125], v[84:85], v[198:199]
	v_pk_fma_f32 v[200:201], v[126:127], v[86:87], v[200:201]
	v_pk_fma_f32 v[202:203], v[124:125], v[80:81], v[202:203]
	v_pk_fma_f32 v[204:205], v[126:127], v[82:83], v[204:205]
	v_pk_fma_f32 v[206:207], v[124:125], v[136:137], v[206:207]
	v_pk_fma_f32 v[208:209], v[126:127], v[138:139], v[208:209]
	v_pk_fma_f32 v[194:195], v[128:129], v[144:145], v[194:195]
	v_pk_fma_f32 v[196:197], v[130:131], v[146:147], v[196:197]
	v_pk_fma_f32 v[198:199], v[128:129], v[148:149], v[198:199]
	v_pk_fma_f32 v[200:201], v[130:131], v[150:151], v[200:201]
	v_pk_fma_f32 v[202:203], v[128:129], v[164:165], v[202:203]
	v_pk_fma_f32 v[204:205], v[130:131], v[166:167], v[204:205]
	v_pk_fma_f32 v[206:207], v[128:129], v[168:169], v[206:207]
	v_pk_fma_f32 v[208:209], v[130:131], v[170:171], v[208:209]
	v_mov_b32_e32 v235, v232
	s_mov_b64 exec, s[12:13]
	global_store_dwordx4 v235, v[140:143], s[16:17] offset:0
	global_store_dwordx4 v235, v[104:107], s[22:23] offset:0
	global_store_dwordx4 v235, v[194:197], s[20:21] offset:0
	s_mov_b64 exec, s[8:9]
	v_add_u32_e32 v235, 0x5800, v235
	s_mov_b64 exec, s[30:31]
	global_store_dwordx4 v235, v[136:139], s[16:17] offset:0
	global_store_dwordx4 v235, v[64:67], s[22:23] offset:0
	global_store_dwordx4 v235, v[206:209], s[20:21] offset:0
	s_mov_b64 exec, s[8:9]
	v_pk_mul_f32 v[144:145], v[194:195], v[194:195]
	v_pk_mul_f32 v[146:147], v[196:197], v[196:197]
	v_pk_mul_f32 v[148:149], v[198:199], v[198:199]
	v_pk_mul_f32 v[150:151], v[200:201], v[200:201]
	v_pk_mul_f32 v[164:165], v[202:203], v[202:203]
	v_pk_mul_f32 v[166:167], v[204:205], v[204:205]
	v_pk_mul_f32 v[168:169], v[206:207], v[206:207]
	v_pk_mul_f32 v[170:171], v[208:209], v[208:209]
	v_pk_fma_f32 v[144:145], v[144:145], v[174:175], v[172:173]
	v_pk_fma_f32 v[146:147], v[146:147], v[174:175], v[172:173]
	v_pk_fma_f32 v[148:149], v[148:149], v[174:175], v[172:173]
	v_pk_fma_f32 v[150:151], v[150:151], v[174:175], v[172:173]
	v_pk_fma_f32 v[164:165], v[164:165], v[174:175], v[172:173]
	v_pk_fma_f32 v[166:167], v[166:167], v[174:175], v[172:173]
	v_pk_fma_f32 v[168:169], v[168:169], v[174:175], v[172:173]
	v_pk_fma_f32 v[170:171], v[170:171], v[174:175], v[172:173]
	v_pk_mul_f32 v[144:145], v[144:145], v[194:195]
	v_pk_mul_f32 v[146:147], v[146:147], v[196:197]
	v_pk_mul_f32 v[148:149], v[148:149], v[198:199]
	v_pk_mul_f32 v[150:151], v[150:151], v[200:201]
	v_pk_mul_f32 v[164:165], v[164:165], v[202:203]
	v_pk_mul_f32 v[166:167], v[166:167], v[204:205]
	v_pk_mul_f32 v[168:169], v[168:169], v[206:207]
	v_pk_mul_f32 v[170:171], v[170:171], v[208:209]
	v_exp_f32_e32 v144, v144
	v_exp_f32_e32 v146, v146
	v_exp_f32_e32 v148, v148
	v_exp_f32_e32 v150, v150
	v_exp_f32_e32 v164, v164
	v_exp_f32_e32 v166, v166
	v_exp_f32_e32 v168, v168
	v_exp_f32_e32 v170, v170
	v_exp_f32_e32 v145, v145
	v_exp_f32_e32 v147, v147
	v_exp_f32_e32 v149, v149
	v_exp_f32_e32 v151, v151
	v_exp_f32_e32 v165, v165
	v_exp_f32_e32 v167, v167
	v_exp_f32_e32 v169, v169
	v_exp_f32_e32 v171, v171
	v_pk_add_f32 v[144:145], v[144:145], v[210:211]
	v_pk_add_f32 v[146:147], v[146:147], v[210:211]
	v_pk_add_f32 v[148:149], v[148:149], v[210:211]
	v_pk_add_f32 v[150:151], v[150:151], v[210:211]
	v_pk_add_f32 v[164:165], v[164:165], v[210:211]
	v_pk_add_f32 v[166:167], v[166:167], v[210:211]
	v_pk_add_f32 v[168:169], v[168:169], v[210:211]
	v_pk_add_f32 v[170:171], v[170:171], v[210:211]
	v_rcp_f32_e32 v144, v144
	v_rcp_f32_e32 v146, v146
	v_rcp_f32_e32 v148, v148
	v_rcp_f32_e32 v150, v150
	v_rcp_f32_e32 v164, v164
	v_rcp_f32_e32 v166, v166
	v_rcp_f32_e32 v168, v168
	v_rcp_f32_e32 v170, v170
	v_rcp_f32_e32 v145, v145
	v_rcp_f32_e32 v147, v147
	v_rcp_f32_e32 v149, v149
	v_rcp_f32_e32 v151, v151
	v_rcp_f32_e32 v165, v165
	v_rcp_f32_e32 v167, v167
	v_rcp_f32_e32 v169, v169
	v_rcp_f32_e32 v171, v171
	v_pk_mul_f32 v[140:141], v[194:195], v[104:105]
	v_pk_mul_f32 v[142:143], v[196:197], v[106:107]
	v_pk_mul_f32 v[84:85], v[198:199], v[76:77]
	v_pk_mul_f32 v[86:87], v[200:201], v[78:79]
	v_pk_mul_f32 v[80:81], v[202:203], v[72:73]
	v_pk_mul_f32 v[82:83], v[204:205], v[74:75]
	v_pk_mul_f32 v[136:137], v[206:207], v[64:65]
	v_pk_mul_f32 v[138:139], v[208:209], v[66:67]
	v_pk_mul_f32 v[140:141], v[140:141], v[144:145]
	v_pk_mul_f32 v[142:143], v[142:143], v[146:147]
	v_pk_mul_f32 v[84:85], v[84:85], v[148:149]
	v_pk_mul_f32 v[86:87], v[86:87], v[150:151]
	v_pk_mul_f32 v[80:81], v[80:81], v[164:165]
	v_pk_mul_f32 v[82:83], v[82:83], v[166:167]
	v_pk_mul_f32 v[136:137], v[136:137], v[168:169]
	v_pk_mul_f32 v[138:139], v[138:139], v[170:171]
	v_mov_b32_dpp v144, v100 row_ror:15 row_mask:0xf bank_mask:0xf
	v_mov_b32_dpp v145, v101 row_ror:15 row_mask:0xf bank_mask:0xf
	v_mov_b32_dpp v146, v102 row_ror:15 row_mask:0xf bank_mask:0xf
	v_mov_b32_dpp v147, v103 row_ror:15 row_mask:0xf bank_mask:0xf
	v_mov_b32_dpp v198, v116 row_ror:1 row_mask:0xf bank_mask:0xf
	v_mov_b32_dpp v148, v96 row_ror:15 row_mask:0xf bank_mask:0xf
	v_mov_b32_dpp v199, v117 row_ror:1 row_mask:0xf bank_mask:0xf
; #define GAS __attribute__((address_space(1)))
; template <int CTRL> __device__ __forceinline__ float dpp_ror(float v) { return __builtin_bit_cast(float, __builtin_amdgcn_update_dpp(0, __builtin_bit_cast(int, v), CTRL, 0xf, 0xf, false)); }
;     __device__ __forceinline__ void operator()(pg8::f32x4 (&acc)[2][2][4][2], const pg8::Unit& u, int wr_, int wc_, int fr_, int fq_) const {
;     ...
; #pragma unroll
;             for (int n = 0; n < 2; ++n) {
;                 const unsigned hc = hc0 + 4u * (unsigned)n;
;                 const pg8::f32x4 w0 = *(const GAS pg8::f32x4*)&cw[hc], w1 = *(const GAS pg8::f32x4*)&cw[(unsigned)DFF + hc], w2 = *(const GAS pg8::f32x4*)&cw[2u * (unsigned)DFF + hc], bb = *(const GAS pg8::f32x4*)&cb[hc];
;                 if (e0) { *(GAS pg8::f32x4*)&EG[eb0 + hc] = acc[ai][0][0][n]; *(GAS pg8::f32x4*)&EU[eb0 + hc] = acc[ai][1][0][n]; }
;                 if (e3) { *(GAS pg8::f32x4*)&EG[eb3 + hc] = acc[ai][0][3][n]; *(GAS pg8::f32x4*)&EU[eb3 + hc] = acc[ai][1][3][n]; }
; #pragma unroll
;                 for (int j = 0; j < 4; ++j) {
;                     float pr[4], nx[4], gg[4];
; #pragma unroll
;                     for (int m = 0; m < 4; ++m) { gg[m] = acc[ai][0][m][n][j]; pr[m] = dpp_ror<0x121>(gg[m]); nx[m] = dpp_ror<0x12F>(gg[m]); }
; #pragma unroll
;                     for (int m = 0; m < 4; ++m) {
;                         const float pv = fr > 0 ? pr[m] : (m > 0 ? pr[m > 0 ? m - 1 : 0] : 0.f);
;                         const float nv = fr < 15 ? nx[m] : (m < 3 ? nx[m < 3 ? m + 1 : 3] : 0.f);
;                         const float cv = w0[j] * pv + w1[j] * gg[m] + w2[j] * nv + bb[j];
;                         if (m == 0) { if (e0) EP[eb0 + hc + (unsigned)j] = cv; } if (m == 3) { if (e3) EP[eb3 + hc + (unsigned)j] = cv; }
;                         acc[ai][0][m][n][j] = gelu_tanh(cv) * acc[ai][1][m][n][j];
;                     }
;                 }
;                 asm volatile("" ::: "memory"); __builtin_amdgcn_sched_barrier(0);
	v_mov_b32_dpp v149, v97 row_ror:15 row_mask:0xf bank_mask:0xf
	v_mov_b32_dpp v200, v118 row_ror:1 row_mask:0xf bank_mask:0xf
	v_mov_b32_dpp v150, v98 row_ror:15 row_mask:0xf bank_mask:0xf
	v_mov_b32_dpp v201, v119 row_ror:1 row_mask:0xf bank_mask:0xf
	v_mov_b32_dpp v151, v99 row_ror:15 row_mask:0xf bank_mask:0xf
	v_mov_b32_dpp v202, v100 row_ror:1 row_mask:0xf bank_mask:0xf
	v_mov_b32_dpp v164, v112 row_ror:15 row_mask:0xf bank_mask:0xf
	v_mov_b32_dpp v203, v101 row_ror:1 row_mask:0xf bank_mask:0xf
	v_mov_b32_dpp v165, v113 row_ror:15 row_mask:0xf bank_mask:0xf
	v_mov_b32_dpp v204, v102 row_ror:1 row_mask:0xf bank_mask:0xf
	v_mov_b32_dpp v166, v114 row_ror:15 row_mask:0xf bank_mask:0xf
	v_mov_b32_dpp v205, v103 row_ror:1 row_mask:0xf bank_mask:0xf
	v_mov_b32_dpp v167, v115 row_ror:15 row_mask:0xf bank_mask:0xf
	v_mov_b32_dpp v206, v96 row_ror:1 row_mask:0xf bank_mask:0xf
	v_mov_b32_dpp v207, v97 row_ror:1 row_mask:0xf bank_mask:0xf
	v_mov_b32_dpp v208, v98 row_ror:1 row_mask:0xf bank_mask:0xf
	v_mov_b32_dpp v209, v99 row_ror:1 row_mask:0xf bank_mask:0xf
	v_mov_b32_dpp v194, v116 row_shr:1 row_mask:0xf bank_mask:0xf bound_ctrl:0
	v_mov_b32_dpp v144, v116 row_shl:1 row_mask:0xf bank_mask:0xf
	v_mov_b32_dpp v195, v117 row_shr:1 row_mask:0xf bank_mask:0xf bound_ctrl:0
	v_mov_b32_dpp v145, v117 row_shl:1 row_mask:0xf bank_mask:0xf
	v_mov_b32_dpp v196, v118 row_shr:1 row_mask:0xf bank_mask:0xf bound_ctrl:0
	v_mov_b32_dpp v146, v118 row_shl:1 row_mask:0xf bank_mask:0xf
	v_mov_b32_dpp v197, v119 row_shr:1 row_mask:0xf bank_mask:0xf bound_ctrl:0
	v_mov_b32_dpp v147, v119 row_shl:1 row_mask:0xf bank_mask:0xf
	v_mov_b32_dpp v198, v100 row_shr:1 row_mask:0xf bank_mask:0xf
	v_mov_b32_dpp v148, v100 row_shl:1 row_mask:0xf bank_mask:0xf
	v_mov_b32_dpp v199, v101 row_shr:1 row_mask:0xf bank_mask:0xf
	v_mov_b32_dpp v149, v101 row_shl:1 row_mask:0xf bank_mask:0xf
	v_mov_b32_dpp v200, v102 row_shr:1 row_mask:0xf bank_mask:0xf
	v_mov_b32_dpp v150, v102 row_shl:1 row_mask:0xf bank_mask:0xf
	v_mov_b32_dpp v201, v103 row_shr:1 row_mask:0xf bank_mask:0xf
	v_mov_b32_dpp v151, v103 row_shl:1 row_mask:0xf bank_mask:0xf
	v_mov_b32_dpp v202, v96 row_shr:1 row_mask:0xf bank_mask:0xf
	v_mov_b32_dpp v164, v96 row_shl:1 row_mask:0xf bank_mask:0xf
	v_mov_b32_dpp v203, v97 row_shr:1 row_mask:0xf bank_mask:0xf
	v_mov_b32_dpp v165, v97 row_shl:1 row_mask:0xf bank_mask:0xf
	v_mov_b32_dpp v204, v98 row_shr:1 row_mask:0xf bank_mask:0xf
	v_mov_b32_dpp v166, v98 row_shl:1 row_mask:0xf bank_mask:0xf
	v_mov_b32_dpp v205, v99 row_shr:1 row_mask:0xf bank_mask:0xf
	v_mov_b32_dpp v167, v99 row_shl:1 row_mask:0xf bank_mask:0xf
	v_mov_b32_dpp v206, v112 row_shr:1 row_mask:0xf bank_mask:0xf
	v_mov_b32_dpp v168, v112 row_shl:1 row_mask:0xf bank_mask:0xf bound_ctrl:0
	v_mov_b32_dpp v207, v113 row_shr:1 row_mask:0xf bank_mask:0xf
	v_mov_b32_dpp v169, v113 row_shl:1 row_mask:0xf bank_mask:0xf bound_ctrl:0
	v_mov_b32_dpp v208, v114 row_shr:1 row_mask:0xf bank_mask:0xf
	v_mov_b32_dpp v170, v114 row_shl:1 row_mask:0xf bank_mask:0xf bound_ctrl:0
	v_mov_b32_dpp v209, v115 row_shr:1 row_mask:0xf bank_mask:0xf
	v_mov_b32_dpp v171, v115 row_shl:1 row_mask:0xf bank_mask:0xf bound_ctrl:0
	v_pk_fma_f32 v[194:195], v[178:179], v[194:195], v[190:191]
	v_pk_fma_f32 v[196:197], v[180:181], v[196:197], v[192:193]
	v_pk_fma_f32 v[198:199], v[178:179], v[198:199], v[190:191]
	v_pk_fma_f32 v[200:201], v[180:181], v[200:201], v[192:193]
	v_pk_fma_f32 v[202:203], v[178:179], v[202:203], v[190:191]
	v_pk_fma_f32 v[204:205], v[180:181], v[204:205], v[192:193]
	v_pk_fma_f32 v[206:207], v[178:179], v[206:207], v[190:191]
	v_pk_fma_f32 v[208:209], v[180:181], v[208:209], v[192:193]
	v_pk_fma_f32 v[194:195], v[182:183], v[116:117], v[194:195]
	v_pk_fma_f32 v[196:197], v[184:185], v[118:119], v[196:197]
	v_pk_fma_f32 v[198:199], v[182:183], v[100:101], v[198:199]
	v_pk_fma_f32 v[200:201], v[184:185], v[102:103], v[200:201]
	v_pk_fma_f32 v[202:203], v[182:183], v[96:97], v[202:203]
	v_pk_fma_f32 v[204:205], v[184:185], v[98:99], v[204:205]
	v_pk_fma_f32 v[206:207], v[182:183], v[112:113], v[206:207]
	v_pk_fma_f32 v[208:209], v[184:185], v[114:115], v[208:209]
	v_pk_fma_f32 v[194:195], v[186:187], v[144:145], v[194:195]
	v_pk_fma_f32 v[196:197], v[188:189], v[146:147], v[196:197]
	v_pk_fma_f32 v[198:199], v[186:187], v[148:149], v[198:199]
	v_pk_fma_f32 v[200:201], v[188:189], v[150:151], v[200:201]
	v_pk_fma_f32 v[202:203], v[186:187], v[164:165], v[202:203]
	v_pk_fma_f32 v[204:205], v[188:189], v[166:167], v[204:205]
	v_pk_fma_f32 v[206:207], v[186:187], v[168:169], v[206:207]
	v_pk_fma_f32 v[208:209], v[188:189], v[170:171], v[208:209]
	v_mov_b32_e32 v235, v232
	s_mov_b64 exec, s[12:13]
	global_store_dwordx4 v235, v[116:119], s[16:17] offset:16
	global_store_dwordx4 v235, v[108:111], s[22:23] offset:16
	global_store_dwordx4 v235, v[194:197], s[20:21] offset:16
	s_mov_b64 exec, s[8:9]
	v_add_u32_e32 v235, 0x5800, v235
	s_mov_b64 exec, s[30:31]
	global_store_dwordx4 v235, v[112:115], s[16:17] offset:16
	global_store_dwordx4 v235, v[68:71], s[22:23] offset:16
	global_store_dwordx4 v235, v[206:209], s[20:21] offset:16
	s_mov_b64 exec, s[8:9]
	v_pk_mul_f32 v[144:145], v[194:195], v[194:195]
	v_pk_mul_f32 v[146:147], v[196:197], v[196:197]
	v_pk_mul_f32 v[148:149], v[198:199], v[198:199]
	v_pk_mul_f32 v[150:151], v[200:201], v[200:201]
	v_pk_mul_f32 v[164:165], v[202:203], v[202:203]
	v_pk_mul_f32 v[166:167], v[204:205], v[204:205]
	v_pk_mul_f32 v[168:169], v[206:207], v[206:207]
	v_pk_mul_f32 v[170:171], v[208:209], v[208:209]
	v_pk_fma_f32 v[144:145], v[144:145], v[174:175], v[172:173]
	v_pk_fma_f32 v[146:147], v[146:147], v[174:175], v[172:173]
; __device__ __forceinline__ unsigned cvt_pk_bf16(float lo, float hi) { unsigned r; asm volatile("v_cvt_pk_bf16_f32 %0, %1, %2" : "=v"(r) : "v"(lo), "v"(hi)); return r; }
; #define GAS __attribute__((address_space(1)))
; template <int CTRL> __device__ __forceinline__ float dpp_ror(float v) { return __builtin_bit_cast(float, __builtin_amdgcn_update_dpp(0, __builtin_bit_cast(int, v), CTRL, 0xf, 0xf, false)); }
;     __device__ __forceinline__ void operator()(pg8::f32x4 (&acc)[2][2][4][2], const pg8::Unit& u, int wr_, int wc_, int fr_, int fq_) const {
;     ...
;                     for (int m = 0; m < 4; ++m) { gg[m] = acc[ai][0][m][n][j]; pr[m] = dpp_ror<0x121>(gg[m]); nx[m] = dpp_ror<0x12F>(gg[m]); }
; #pragma unroll
;                     for (int m = 0; m < 4; ++m) {
;                         const float pv = fr > 0 ? pr[m] : (m > 0 ? pr[m > 0 ? m - 1 : 0] : 0.f);
;                         const float nv = fr < 15 ? nx[m] : (m < 3 ? nx[m < 3 ? m + 1 : 3] : 0.f);
;                         const float cv = w0[j] * pv + w1[j] * gg[m] + w2[j] * nv + bb[j];
;                         if (m == 0) { if (e0) EP[eb0 + hc + (unsigned)j] = cv; } if (m == 3) { if (e3) EP[eb3 + hc + (unsigned)j] = cv; }
;                         acc[ai][0][m][n][j] = gelu_tanh(cv) * acc[ai][1][m][n][j];
;                     }
;                 }
;                 asm volatile("" ::: "memory"); __builtin_amdgcn_sched_barrier(0);
;             }
; #pragma unroll
;             for (int m = 0; m < 4; ++m) {
;                 if (!((m == 0 && e0) || (m == 3 && e3))) {
;                     const pg8::f32x4 v0 = acc[ai][0][m][0], v1 = acc[ai][0][m][1];
;                     v4u w; w.x = pg8::cvt_pk_bf16(v0[0], v0[1]); w.y = pg8::cvt_pk_bf16(v0[2], v0[3]); w.z = pg8::cvt_pk_bf16(v1[0], v1[1]); w.w = pg8::cvt_pk_bf16(v1[2], v1[3]);
;                     *(GAS v4u*)&HID[(unsigned)(rbase + m * 16 + fr) * (unsigned)DFF + hc0] = w;
	v_pk_fma_f32 v[148:149], v[148:149], v[174:175], v[172:173]
	v_pk_fma_f32 v[150:151], v[150:151], v[174:175], v[172:173]
	v_pk_fma_f32 v[164:165], v[164:165], v[174:175], v[172:173]
	v_pk_fma_f32 v[166:167], v[166:167], v[174:175], v[172:173]
	v_pk_fma_f32 v[168:169], v[168:169], v[174:175], v[172:173]
	v_pk_fma_f32 v[170:171], v[170:171], v[174:175], v[172:173]
	v_pk_mul_f32 v[144:145], v[144:145], v[194:195]
	v_pk_mul_f32 v[146:147], v[146:147], v[196:197]
	v_pk_mul_f32 v[148:149], v[148:149], v[198:199]
	v_pk_mul_f32 v[150:151], v[150:151], v[200:201]
	v_pk_mul_f32 v[164:165], v[164:165], v[202:203]
	v_pk_mul_f32 v[166:167], v[166:167], v[204:205]
	v_pk_mul_f32 v[168:169], v[168:169], v[206:207]
	v_pk_mul_f32 v[170:171], v[170:171], v[208:209]
	v_exp_f32_e32 v144, v144
	v_exp_f32_e32 v146, v146
	v_exp_f32_e32 v148, v148
	v_exp_f32_e32 v150, v150
	v_exp_f32_e32 v164, v164
	v_exp_f32_e32 v166, v166
	v_exp_f32_e32 v168, v168
	v_exp_f32_e32 v170, v170
	v_exp_f32_e32 v145, v145
	v_exp_f32_e32 v147, v147
	v_exp_f32_e32 v149, v149
	v_exp_f32_e32 v151, v151
	v_exp_f32_e32 v165, v165
	v_exp_f32_e32 v167, v167
	v_exp_f32_e32 v169, v169
	v_exp_f32_e32 v171, v171
	v_pk_add_f32 v[144:145], v[144:145], v[210:211]
	v_pk_add_f32 v[146:147], v[146:147], v[210:211]
	v_pk_add_f32 v[148:149], v[148:149], v[210:211]
	v_pk_add_f32 v[150:151], v[150:151], v[210:211]
	v_pk_add_f32 v[164:165], v[164:165], v[210:211]
	v_pk_add_f32 v[166:167], v[166:167], v[210:211]
	v_pk_add_f32 v[168:169], v[168:169], v[210:211]
	v_pk_add_f32 v[170:171], v[170:171], v[210:211]
	v_rcp_f32_e32 v144, v144
	v_rcp_f32_e32 v146, v146
	v_rcp_f32_e32 v148, v148
	v_rcp_f32_e32 v150, v150
	v_rcp_f32_e32 v164, v164
	v_rcp_f32_e32 v166, v166
	v_rcp_f32_e32 v168, v168
	v_rcp_f32_e32 v170, v170
	v_rcp_f32_e32 v145, v145
	v_rcp_f32_e32 v147, v147
	v_rcp_f32_e32 v149, v149
	v_rcp_f32_e32 v151, v151
	v_rcp_f32_e32 v165, v165
	v_rcp_f32_e32 v167, v167
	v_rcp_f32_e32 v169, v169
	v_rcp_f32_e32 v171, v171
	v_pk_mul_f32 v[116:117], v[194:195], v[108:109]
	v_pk_mul_f32 v[118:119], v[196:197], v[110:111]
	v_pk_mul_f32 v[100:101], v[198:199], v[92:93]
	v_pk_mul_f32 v[102:103], v[200:201], v[94:95]
	v_pk_mul_f32 v[96:97], v[202:203], v[88:89]
	v_pk_mul_f32 v[98:99], v[204:205], v[90:91]
	v_pk_mul_f32 v[112:113], v[206:207], v[68:69]
	v_pk_mul_f32 v[114:115], v[208:209], v[70:71]
	v_pk_mul_f32 v[116:117], v[116:117], v[144:145]
	v_pk_mul_f32 v[118:119], v[118:119], v[146:147]
	v_pk_mul_f32 v[100:101], v[100:101], v[148:149]
	v_pk_mul_f32 v[102:103], v[102:103], v[150:151]
	v_pk_mul_f32 v[96:97], v[96:97], v[164:165]
	v_pk_mul_f32 v[98:99], v[98:99], v[166:167]
	v_pk_mul_f32 v[112:113], v[112:113], v[168:169]
	v_pk_mul_f32 v[114:115], v[114:115], v[170:171]
	v_cvt_pk_bf16_f32 v140, v140, v141
	v_cvt_pk_bf16_f32 v141, v142, v143
	v_cvt_pk_bf16_f32 v142, v116, v117
	v_cvt_pk_bf16_f32 v143, v118, v119
	v_cvt_pk_bf16_f32 v84, v84, v85
	v_cvt_pk_bf16_f32 v85, v86, v87
	v_cvt_pk_bf16_f32 v86, v100, v101
	v_cvt_pk_bf16_f32 v87, v102, v103
	v_cvt_pk_bf16_f32 v80, v80, v81
	v_cvt_pk_bf16_f32 v81, v82, v83
	v_cvt_pk_bf16_f32 v82, v96, v97
	v_cvt_pk_bf16_f32 v83, v98, v99
	v_cvt_pk_bf16_f32 v136, v136, v137
	v_cvt_pk_bf16_f32 v137, v138, v139
	v_cvt_pk_bf16_f32 v138, v112, v113
	v_cvt_pk_bf16_f32 v139, v114, v115
	v_mov_b32_e32 v235, v233
	s_mov_b64 exec, s[10:11]
	global_store_dwordx4 v235, v[140:143], s[18:19]
	s_mov_b64 exec, s[8:9]
	v_add_u32_e32 v235, 0x2c000, v233
	global_store_dwordx4 v235, v[84:87], s[18:19]
	v_add_u32_e32 v235, 0x58000, v233
	global_store_dwordx4 v235, v[80:83], s[18:19]
	v_add_u32_e32 v235, 0x84000, v233
	s_mov_b64 exec, s[62:63]
	global_store_dwordx4 v235, v[136:139], s[18:19]
	s_mov_b64 exec, s[8:9]
	v_mov_b32_dpp v144, v20 row_ror:15 row_mask:0xf bank_mask:0xf
	v_mov_b32_dpp v145, v21 row_ror:15 row_mask:0xf bank_mask:0xf
	v_mov_b32_dpp v146, v22 row_ror:15 row_mask:0xf bank_mask:0xf
	v_mov_b32_dpp v147, v23 row_ror:15 row_mask:0xf bank_mask:0xf
	v_mov_b32_dpp v198, v60 row_ror:1 row_mask:0xf bank_mask:0xf
	v_mov_b32_dpp v148, v16 row_ror:15 row_mask:0xf bank_mask:0xf
	v_mov_b32_dpp v199, v61 row_ror:1 row_mask:0xf bank_mask:0xf
	v_mov_b32_dpp v149, v17 row_ror:15 row_mask:0xf bank_mask:0xf
	v_mov_b32_dpp v200, v62 row_ror:1 row_mask:0xf bank_mask:0xf
	v_mov_b32_dpp v150, v18 row_ror:15 row_mask:0xf bank_mask:0xf
	v_mov_b32_dpp v201, v63 row_ror:1 row_mask:0xf bank_mask:0xf
	v_mov_b32_dpp v151, v19 row_ror:15 row_mask:0xf bank_mask:0xf
	v_mov_b32_dpp v202, v20 row_ror:1 row_mask:0xf bank_mask:0xf
	v_mov_b32_dpp v164, v56 row_ror:15 row_mask:0xf bank_mask:0xf
	v_mov_b32_dpp v203, v21 row_ror:1 row_mask:0xf bank_mask:0xf
	v_mov_b32_dpp v165, v57 row_ror:15 row_mask:0xf bank_mask:0xf
	v_mov_b32_dpp v204, v22 row_ror:1 row_mask:0xf bank_mask:0xf
	v_mov_b32_dpp v166, v58 row_ror:15 row_mask:0xf bank_mask:0xf
	v_mov_b32_dpp v205, v23 row_ror:1 row_mask:0xf bank_mask:0xf
	v_mov_b32_dpp v167, v59 row_ror:15 row_mask:0xf bank_mask:0xf
	v_mov_b32_dpp v206, v16 row_ror:1 row_mask:0xf bank_mask:0xf
	v_mov_b32_dpp v207, v17 row_ror:1 row_mask:0xf bank_mask:0xf
	v_mov_b32_dpp v208, v18 row_ror:1 row_mask:0xf bank_mask:0xf
	v_mov_b32_dpp v209, v19 row_ror:1 row_mask:0xf bank_mask:0xf
	v_mov_b32_dpp v194, v60 row_shr:1 row_mask:0xf bank_mask:0xf bound_ctrl:0
	v_mov_b32_dpp v144, v60 row_shl:1 row_mask:0xf bank_mask:0xf
	v_mov_b32_dpp v195, v61 row_shr:1 row_mask:0xf bank_mask:0xf bound_ctrl:0
	v_mov_b32_dpp v145, v61 row_shl:1 row_mask:0xf bank_mask:0xf
	v_mov_b32_dpp v196, v62 row_shr:1 row_mask:0xf bank_mask:0xf bound_ctrl:0
	v_mov_b32_dpp v146, v62 row_shl:1 row_mask:0xf bank_mask:0xf
; #define GAS __attribute__((address_space(1)))
; template <int CTRL> __device__ __forceinline__ float dpp_ror(float v) { return __builtin_bit_cast(float, __builtin_amdgcn_update_dpp(0, __builtin_bit_cast(int, v), CTRL, 0xf, 0xf, false)); }
;     __device__ __forceinline__ void operator()(pg8::f32x4 (&acc)[2][2][4][2], const pg8::Unit& u, int wr_, int wc_, int fr_, int fq_) const {
;     ...
;                 const pg8::f32x4 w0 = *(const GAS pg8::f32x4*)&cw[hc], w1 = *(const GAS pg8::f32x4*)&cw[(unsigned)DFF + hc], w2 = *(const GAS pg8::f32x4*)&cw[2u * (unsigned)DFF + hc], bb = *(const GAS pg8::f32x4*)&cb[hc];
;                 if (e0) { *(GAS pg8::f32x4*)&EG[eb0 + hc] = acc[ai][0][0][n]; *(GAS pg8::f32x4*)&EU[eb0 + hc] = acc[ai][1][0][n]; }
;                 if (e3) { *(GAS pg8::f32x4*)&EG[eb3 + hc] = acc[ai][0][3][n]; *(GAS pg8::f32x4*)&EU[eb3 + hc] = acc[ai][1][3][n]; }
; #pragma unroll
;                 for (int j = 0; j < 4; ++j) {
;                     float pr[4], nx[4], gg[4];
; #pragma unroll
;                     for (int m = 0; m < 4; ++m) { gg[m] = acc[ai][0][m][n][j]; pr[m] = dpp_ror<0x121>(gg[m]); nx[m] = dpp_ror<0x12F>(gg[m]); }
; #pragma unroll
;                     for (int m = 0; m < 4; ++m) {
;                         const float pv = fr > 0 ? pr[m] : (m > 0 ? pr[m > 0 ? m - 1 : 0] : 0.f);
;                         const float nv = fr < 15 ? nx[m] : (m < 3 ? nx[m < 3 ? m + 1 : 3] : 0.f);
;                         const float cv = w0[j] * pv + w1[j] * gg[m] + w2[j] * nv + bb[j];
;                         if (m == 0) { if (e0) EP[eb0 + hc + (unsigned)j] = cv; } if (m == 3) { if (e3) EP[eb3 + hc + (unsigned)j] = cv; }
;                         acc[ai][0][m][n][j] = gelu_tanh(cv) * acc[ai][1][m][n][j];
;                     }
;                 }
;                 asm volatile("" ::: "memory"); __builtin_amdgcn_sched_barrier(0);
	v_mov_b32_dpp v197, v63 row_shr:1 row_mask:0xf bank_mask:0xf bound_ctrl:0
	v_mov_b32_dpp v147, v63 row_shl:1 row_mask:0xf bank_mask:0xf
	v_mov_b32_dpp v198, v20 row_shr:1 row_mask:0xf bank_mask:0xf
	v_mov_b32_dpp v148, v20 row_shl:1 row_mask:0xf bank_mask:0xf
	v_mov_b32_dpp v199, v21 row_shr:1 row_mask:0xf bank_mask:0xf
	v_mov_b32_dpp v149, v21 row_shl:1 row_mask:0xf bank_mask:0xf
	v_mov_b32_dpp v200, v22 row_shr:1 row_mask:0xf bank_mask:0xf
	v_mov_b32_dpp v150, v22 row_shl:1 row_mask:0xf bank_mask:0xf
	v_mov_b32_dpp v201, v23 row_shr:1 row_mask:0xf bank_mask:0xf
	v_mov_b32_dpp v151, v23 row_shl:1 row_mask:0xf bank_mask:0xf
	v_mov_b32_dpp v202, v16 row_shr:1 row_mask:0xf bank_mask:0xf
	v_mov_b32_dpp v164, v16 row_shl:1 row_mask:0xf bank_mask:0xf
	v_mov_b32_dpp v203, v17 row_shr:1 row_mask:0xf bank_mask:0xf
	v_mov_b32_dpp v165, v17 row_shl:1 row_mask:0xf bank_mask:0xf
	v_mov_b32_dpp v204, v18 row_shr:1 row_mask:0xf bank_mask:0xf
	v_mov_b32_dpp v166, v18 row_shl:1 row_mask:0xf bank_mask:0xf
	v_mov_b32_dpp v205, v19 row_shr:1 row_mask:0xf bank_mask:0xf
	v_mov_b32_dpp v167, v19 row_shl:1 row_mask:0xf bank_mask:0xf
	v_mov_b32_dpp v206, v56 row_shr:1 row_mask:0xf bank_mask:0xf
	v_mov_b32_dpp v168, v56 row_shl:1 row_mask:0xf bank_mask:0xf bound_ctrl:0
	v_mov_b32_dpp v207, v57 row_shr:1 row_mask:0xf bank_mask:0xf
	v_mov_b32_dpp v169, v57 row_shl:1 row_mask:0xf bank_mask:0xf bound_ctrl:0
	v_mov_b32_dpp v208, v58 row_shr:1 row_mask:0xf bank_mask:0xf
	v_mov_b32_dpp v170, v58 row_shl:1 row_mask:0xf bank_mask:0xf bound_ctrl:0
	v_mov_b32_dpp v209, v59 row_shr:1 row_mask:0xf bank_mask:0xf
	v_mov_b32_dpp v171, v59 row_shl:1 row_mask:0xf bank_mask:0xf bound_ctrl:0
	v_pk_fma_f32 v[194:195], v[120:121], v[194:195], v[132:133]
	v_pk_fma_f32 v[196:197], v[122:123], v[196:197], v[134:135]
	v_pk_fma_f32 v[198:199], v[120:121], v[198:199], v[132:133]
	v_pk_fma_f32 v[200:201], v[122:123], v[200:201], v[134:135]
	v_pk_fma_f32 v[202:203], v[120:121], v[202:203], v[132:133]
	v_pk_fma_f32 v[204:205], v[122:123], v[204:205], v[134:135]
	v_pk_fma_f32 v[206:207], v[120:121], v[206:207], v[132:133]
	v_pk_fma_f32 v[208:209], v[122:123], v[208:209], v[134:135]
	v_pk_fma_f32 v[194:195], v[124:125], v[60:61], v[194:195]
	v_pk_fma_f32 v[196:197], v[126:127], v[62:63], v[196:197]
	v_pk_fma_f32 v[198:199], v[124:125], v[20:21], v[198:199]
	v_pk_fma_f32 v[200:201], v[126:127], v[22:23], v[200:201]
	v_pk_fma_f32 v[202:203], v[124:125], v[16:17], v[202:203]
	v_pk_fma_f32 v[204:205], v[126:127], v[18:19], v[204:205]
	v_pk_fma_f32 v[206:207], v[124:125], v[56:57], v[206:207]
	v_pk_fma_f32 v[208:209], v[126:127], v[58:59], v[208:209]
	v_pk_fma_f32 v[194:195], v[128:129], v[144:145], v[194:195]
	v_pk_fma_f32 v[196:197], v[130:131], v[146:147], v[196:197]
	v_pk_fma_f32 v[198:199], v[128:129], v[148:149], v[198:199]
	v_pk_fma_f32 v[200:201], v[130:131], v[150:151], v[200:201]
	v_pk_fma_f32 v[202:203], v[128:129], v[164:165], v[202:203]
	v_pk_fma_f32 v[204:205], v[130:131], v[166:167], v[204:205]
	v_pk_fma_f32 v[206:207], v[128:129], v[168:169], v[206:207]
	v_pk_fma_f32 v[208:209], v[130:131], v[170:171], v[208:209]
	v_add_u32_e32 v235, 0x16000, v232
	s_mov_b64 exec, s[12:13]
	global_store_dwordx4 v235, v[60:63], s[16:17] offset:0
	global_store_dwordx4 v235, v[40:43], s[22:23] offset:0
	global_store_dwordx4 v235, v[194:197], s[20:21] offset:0
	s_mov_b64 exec, s[8:9]
	v_add_u32_e32 v235, 0x5800, v235
	s_mov_b64 exec, s[30:31]
	global_store_dwordx4 v235, v[56:59], s[16:17] offset:0
	global_store_dwordx4 v235, v[0:3], s[22:23] offset:0
	global_store_dwordx4 v235, v[206:209], s[20:21] offset:0
	s_mov_b64 exec, s[8:9]
	v_pk_mul_f32 v[144:145], v[194:195], v[194:195]
	v_pk_mul_f32 v[146:147], v[196:197], v[196:197]
	v_pk_mul_f32 v[148:149], v[198:199], v[198:199]
	v_pk_mul_f32 v[150:151], v[200:201], v[200:201]
	v_pk_mul_f32 v[164:165], v[202:203], v[202:203]
	v_pk_mul_f32 v[166:167], v[204:205], v[204:205]
	v_pk_mul_f32 v[168:169], v[206:207], v[206:207]
	v_pk_mul_f32 v[170:171], v[208:209], v[208:209]
	v_pk_fma_f32 v[144:145], v[144:145], v[174:175], v[172:173]
	v_pk_fma_f32 v[146:147], v[146:147], v[174:175], v[172:173]
	v_pk_fma_f32 v[148:149], v[148:149], v[174:175], v[172:173]
	v_pk_fma_f32 v[150:151], v[150:151], v[174:175], v[172:173]
	v_pk_fma_f32 v[164:165], v[164:165], v[174:175], v[172:173]
	v_pk_fma_f32 v[166:167], v[166:167], v[174:175], v[172:173]
	v_pk_fma_f32 v[168:169], v[168:169], v[174:175], v[172:173]
	v_pk_fma_f32 v[170:171], v[170:171], v[174:175], v[172:173]
	v_pk_mul_f32 v[144:145], v[144:145], v[194:195]
	v_pk_mul_f32 v[146:147], v[146:147], v[196:197]
	v_pk_mul_f32 v[148:149], v[148:149], v[198:199]
	v_pk_mul_f32 v[150:151], v[150:151], v[200:201]
	v_pk_mul_f32 v[164:165], v[164:165], v[202:203]
	v_pk_mul_f32 v[166:167], v[166:167], v[204:205]
	v_pk_mul_f32 v[168:169], v[168:169], v[206:207]
	v_pk_mul_f32 v[170:171], v[170:171], v[208:209]
	v_exp_f32_e32 v144, v144
	v_exp_f32_e32 v146, v146
	v_exp_f32_e32 v148, v148
	v_exp_f32_e32 v150, v150
	v_exp_f32_e32 v164, v164
	v_exp_f32_e32 v166, v166
	v_exp_f32_e32 v168, v168
	v_exp_f32_e32 v170, v170
	v_exp_f32_e32 v145, v145
	v_exp_f32_e32 v147, v147
	v_exp_f32_e32 v149, v149
	v_exp_f32_e32 v151, v151
	v_exp_f32_e32 v165, v165
	v_exp_f32_e32 v167, v167
	v_exp_f32_e32 v169, v169
	v_exp_f32_e32 v171, v171
	v_pk_add_f32 v[144:145], v[144:145], v[210:211]
	v_pk_add_f32 v[146:147], v[146:147], v[210:211]
	v_pk_add_f32 v[148:149], v[148:149], v[210:211]
	v_pk_add_f32 v[150:151], v[150:151], v[210:211]
	v_pk_add_f32 v[164:165], v[164:165], v[210:211]
	v_pk_add_f32 v[166:167], v[166:167], v[210:211]
	v_pk_add_f32 v[168:169], v[168:169], v[210:211]
; template <int CTRL> __device__ __forceinline__ float dpp_ror(float v) { return __builtin_bit_cast(float, __builtin_amdgcn_update_dpp(0, __builtin_bit_cast(int, v), CTRL, 0xf, 0xf, false)); }
;     __device__ __forceinline__ void operator()(pg8::f32x4 (&acc)[2][2][4][2], const pg8::Unit& u, int wr_, int wc_, int fr_, int fq_) const {
;     ...
;                     for (int m = 0; m < 4; ++m) { gg[m] = acc[ai][0][m][n][j]; pr[m] = dpp_ror<0x121>(gg[m]); nx[m] = dpp_ror<0x12F>(gg[m]); }
; #pragma unroll
;                     for (int m = 0; m < 4; ++m) {
;                         const float pv = fr > 0 ? pr[m] : (m > 0 ? pr[m > 0 ? m - 1 : 0] : 0.f);
;                         const float nv = fr < 15 ? nx[m] : (m < 3 ? nx[m < 3 ? m + 1 : 3] : 0.f);
;                         const float cv = w0[j] * pv + w1[j] * gg[m] + w2[j] * nv + bb[j];
;                         if (m == 0) { if (e0) EP[eb0 + hc + (unsigned)j] = cv; } if (m == 3) { if (e3) EP[eb3 + hc + (unsigned)j] = cv; }
;                         acc[ai][0][m][n][j] = gelu_tanh(cv) * acc[ai][1][m][n][j];
;                     }
;                 }
;                 asm volatile("" ::: "memory"); __builtin_amdgcn_sched_barrier(0);
	v_pk_add_f32 v[170:171], v[170:171], v[210:211]
	v_rcp_f32_e32 v144, v144
	v_rcp_f32_e32 v146, v146
	v_rcp_f32_e32 v148, v148
	v_rcp_f32_e32 v150, v150
	v_rcp_f32_e32 v164, v164
	v_rcp_f32_e32 v166, v166
	v_rcp_f32_e32 v168, v168
	v_rcp_f32_e32 v170, v170
	v_rcp_f32_e32 v145, v145
	v_rcp_f32_e32 v147, v147
	v_rcp_f32_e32 v149, v149
	v_rcp_f32_e32 v151, v151
	v_rcp_f32_e32 v165, v165
	v_rcp_f32_e32 v167, v167
	v_rcp_f32_e32 v169, v169
	v_rcp_f32_e32 v171, v171
	v_pk_mul_f32 v[60:61], v[194:195], v[40:41]
	v_pk_mul_f32 v[62:63], v[196:197], v[42:43]
	v_pk_mul_f32 v[20:21], v[198:199], v[12:13]
	v_pk_mul_f32 v[22:23], v[200:201], v[14:15]
	v_pk_mul_f32 v[16:17], v[202:203], v[8:9]
	v_pk_mul_f32 v[18:19], v[204:205], v[10:11]
	v_pk_mul_f32 v[56:57], v[206:207], v[0:1]
	v_pk_mul_f32 v[58:59], v[208:209], v[2:3]
	v_pk_mul_f32 v[60:61], v[60:61], v[144:145]
	v_pk_mul_f32 v[62:63], v[62:63], v[146:147]
	v_pk_mul_f32 v[20:21], v[20:21], v[148:149]
	v_pk_mul_f32 v[22:23], v[22:23], v[150:151]
	v_pk_mul_f32 v[16:17], v[16:17], v[164:165]
	v_pk_mul_f32 v[18:19], v[18:19], v[166:167]
	v_pk_mul_f32 v[56:57], v[56:57], v[168:169]
	v_pk_mul_f32 v[58:59], v[58:59], v[170:171]
	v_mov_b32_dpp v144, v36 row_ror:15 row_mask:0xf bank_mask:0xf
	v_mov_b32_dpp v145, v37 row_ror:15 row_mask:0xf bank_mask:0xf
	v_mov_b32_dpp v146, v38 row_ror:15 row_mask:0xf bank_mask:0xf
	v_mov_b32_dpp v147, v39 row_ror:15 row_mask:0xf bank_mask:0xf
	v_mov_b32_dpp v198, v52 row_ror:1 row_mask:0xf bank_mask:0xf
	v_mov_b32_dpp v148, v32 row_ror:15 row_mask:0xf bank_mask:0xf
	v_mov_b32_dpp v199, v53 row_ror:1 row_mask:0xf bank_mask:0xf
	v_mov_b32_dpp v149, v33 row_ror:15 row_mask:0xf bank_mask:0xf
	v_mov_b32_dpp v200, v54 row_ror:1 row_mask:0xf bank_mask:0xf
	v_mov_b32_dpp v150, v34 row_ror:15 row_mask:0xf bank_mask:0xf
	v_mov_b32_dpp v201, v55 row_ror:1 row_mask:0xf bank_mask:0xf
	v_mov_b32_dpp v151, v35 row_ror:15 row_mask:0xf bank_mask:0xf
	v_mov_b32_dpp v202, v36 row_ror:1 row_mask:0xf bank_mask:0xf
	v_mov_b32_dpp v164, v48 row_ror:15 row_mask:0xf bank_mask:0xf
	v_mov_b32_dpp v203, v37 row_ror:1 row_mask:0xf bank_mask:0xf
	v_mov_b32_dpp v165, v49 row_ror:15 row_mask:0xf bank_mask:0xf
	v_mov_b32_dpp v204, v38 row_ror:1 row_mask:0xf bank_mask:0xf
	v_mov_b32_dpp v166, v50 row_ror:15 row_mask:0xf bank_mask:0xf
	v_mov_b32_dpp v205, v39 row_ror:1 row_mask:0xf bank_mask:0xf
	v_mov_b32_dpp v167, v51 row_ror:15 row_mask:0xf bank_mask:0xf
	v_mov_b32_dpp v206, v32 row_ror:1 row_mask:0xf bank_mask:0xf
	v_mov_b32_dpp v207, v33 row_ror:1 row_mask:0xf bank_mask:0xf
	v_mov_b32_dpp v208, v34 row_ror:1 row_mask:0xf bank_mask:0xf
	v_mov_b32_dpp v209, v35 row_ror:1 row_mask:0xf bank_mask:0xf
	v_mov_b32_dpp v194, v52 row_shr:1 row_mask:0xf bank_mask:0xf bound_ctrl:0
	v_mov_b32_dpp v144, v52 row_shl:1 row_mask:0xf bank_mask:0xf
	v_mov_b32_dpp v195, v53 row_shr:1 row_mask:0xf bank_mask:0xf bound_ctrl:0
	v_mov_b32_dpp v145, v53 row_shl:1 row_mask:0xf bank_mask:0xf
	v_mov_b32_dpp v196, v54 row_shr:1 row_mask:0xf bank_mask:0xf bound_ctrl:0
	v_mov_b32_dpp v146, v54 row_shl:1 row_mask:0xf bank_mask:0xf
	v_mov_b32_dpp v197, v55 row_shr:1 row_mask:0xf bank_mask:0xf bound_ctrl:0
	v_mov_b32_dpp v147, v55 row_shl:1 row_mask:0xf bank_mask:0xf
	v_mov_b32_dpp v198, v36 row_shr:1 row_mask:0xf bank_mask:0xf
	v_mov_b32_dpp v148, v36 row_shl:1 row_mask:0xf bank_mask:0xf
	v_mov_b32_dpp v199, v37 row_shr:1 row_mask:0xf bank_mask:0xf
	v_mov_b32_dpp v149, v37 row_shl:1 row_mask:0xf bank_mask:0xf
	v_mov_b32_dpp v200, v38 row_shr:1 row_mask:0xf bank_mask:0xf
	v_mov_b32_dpp v150, v38 row_shl:1 row_mask:0xf bank_mask:0xf
	v_mov_b32_dpp v201, v39 row_shr:1 row_mask:0xf bank_mask:0xf
	v_mov_b32_dpp v151, v39 row_shl:1 row_mask:0xf bank_mask:0xf
	v_mov_b32_dpp v202, v32 row_shr:1 row_mask:0xf bank_mask:0xf
	v_mov_b32_dpp v164, v32 row_shl:1 row_mask:0xf bank_mask:0xf
	v_mov_b32_dpp v203, v33 row_shr:1 row_mask:0xf bank_mask:0xf
	v_mov_b32_dpp v165, v33 row_shl:1 row_mask:0xf bank_mask:0xf
	v_mov_b32_dpp v204, v34 row_shr:1 row_mask:0xf bank_mask:0xf
	v_mov_b32_dpp v166, v34 row_shl:1 row_mask:0xf bank_mask:0xf
	v_mov_b32_dpp v205, v35 row_shr:1 row_mask:0xf bank_mask:0xf
	v_mov_b32_dpp v167, v35 row_shl:1 row_mask:0xf bank_mask:0xf
	v_mov_b32_dpp v206, v48 row_shr:1 row_mask:0xf bank_mask:0xf
	v_mov_b32_dpp v168, v48 row_shl:1 row_mask:0xf bank_mask:0xf bound_ctrl:0
	v_mov_b32_dpp v207, v49 row_shr:1 row_mask:0xf bank_mask:0xf
	v_mov_b32_dpp v169, v49 row_shl:1 row_mask:0xf bank_mask:0xf bound_ctrl:0
	v_mov_b32_dpp v208, v50 row_shr:1 row_mask:0xf bank_mask:0xf
	v_mov_b32_dpp v170, v50 row_shl:1 row_mask:0xf bank_mask:0xf bound_ctrl:0
	v_mov_b32_dpp v209, v51 row_shr:1 row_mask:0xf bank_mask:0xf
	v_mov_b32_dpp v171, v51 row_shl:1 row_mask:0xf bank_mask:0xf bound_ctrl:0
	v_pk_fma_f32 v[194:195], v[178:179], v[194:195], v[190:191]
	v_pk_fma_f32 v[196:197], v[180:181], v[196:197], v[192:193]
	v_pk_fma_f32 v[198:199], v[178:179], v[198:199], v[190:191]
	v_pk_fma_f32 v[200:201], v[180:181], v[200:201], v[192:193]
	v_pk_fma_f32 v[202:203], v[178:179], v[202:203], v[190:191]
	v_pk_fma_f32 v[204:205], v[180:181], v[204:205], v[192:193]
	v_pk_fma_f32 v[206:207], v[178:179], v[206:207], v[190:191]
	v_pk_fma_f32 v[208:209], v[180:181], v[208:209], v[192:193]
	v_pk_fma_f32 v[194:195], v[182:183], v[52:53], v[194:195]
	v_pk_fma_f32 v[196:197], v[184:185], v[54:55], v[196:197]
	v_pk_fma_f32 v[198:199], v[182:183], v[36:37], v[198:199]
; __device__ __forceinline__ unsigned cvt_pk_bf16(float lo, float hi) { unsigned r; asm volatile("v_cvt_pk_bf16_f32 %0, %1, %2" : "=v"(r) : "v"(lo), "v"(hi)); return r; }
; #define GAS __attribute__((address_space(1)))
; template <int CTRL> __device__ __forceinline__ float dpp_ror(float v) { return __builtin_bit_cast(float, __builtin_amdgcn_update_dpp(0, __builtin_bit_cast(int, v), CTRL, 0xf, 0xf, false)); }
;     __device__ __forceinline__ void operator()(pg8::f32x4 (&acc)[2][2][4][2], const pg8::Unit& u, int wr_, int wc_, int fr_, int fq_) const {
;     ...
;                 if (e0) { *(GAS pg8::f32x4*)&EG[eb0 + hc] = acc[ai][0][0][n]; *(GAS pg8::f32x4*)&EU[eb0 + hc] = acc[ai][1][0][n]; }
;                 if (e3) { *(GAS pg8::f32x4*)&EG[eb3 + hc] = acc[ai][0][3][n]; *(GAS pg8::f32x4*)&EU[eb3 + hc] = acc[ai][1][3][n]; }
; #pragma unroll
;                 for (int j = 0; j < 4; ++j) {
;                     float pr[4], nx[4], gg[4];
; #pragma unroll
;                     for (int m = 0; m < 4; ++m) { gg[m] = acc[ai][0][m][n][j]; pr[m] = dpp_ror<0x121>(gg[m]); nx[m] = dpp_ror<0x12F>(gg[m]); }
; #pragma unroll
;                     for (int m = 0; m < 4; ++m) {
;                         const float pv = fr > 0 ? pr[m] : (m > 0 ? pr[m > 0 ? m - 1 : 0] : 0.f);
;                         const float nv = fr < 15 ? nx[m] : (m < 3 ? nx[m < 3 ? m + 1 : 3] : 0.f);
;                         const float cv = w0[j] * pv + w1[j] * gg[m] + w2[j] * nv + bb[j];
;                         if (m == 0) { if (e0) EP[eb0 + hc + (unsigned)j] = cv; } if (m == 3) { if (e3) EP[eb3 + hc + (unsigned)j] = cv; }
;                         acc[ai][0][m][n][j] = gelu_tanh(cv) * acc[ai][1][m][n][j];
;                     }
;                 }
;                 asm volatile("" ::: "memory"); __builtin_amdgcn_sched_barrier(0);
;             }
; #pragma unroll
;             for (int m = 0; m < 4; ++m) {
;                 if (!((m == 0 && e0) || (m == 3 && e3))) {
;                     const pg8::f32x4 v0 = acc[ai][0][m][0], v1 = acc[ai][0][m][1];
;                     v4u w; w.x = pg8::cvt_pk_bf16(v0[0], v0[1]); w.y = pg8::cvt_pk_bf16(v0[2], v0[3]); w.z = pg8::cvt_pk_bf16(v1[0], v1[1]); w.w = pg8::cvt_pk_bf16(v1[2], v1[3]);
;                     *(GAS v4u*)&HID[(unsigned)(rbase + m * 16 + fr) * (unsigned)DFF + hc0] = w;
	v_pk_fma_f32 v[200:201], v[184:185], v[38:39], v[200:201]
	v_pk_fma_f32 v[202:203], v[182:183], v[32:33], v[202:203]
	v_pk_fma_f32 v[204:205], v[184:185], v[34:35], v[204:205]
	v_pk_fma_f32 v[206:207], v[182:183], v[48:49], v[206:207]
	v_pk_fma_f32 v[208:209], v[184:185], v[50:51], v[208:209]
	v_pk_fma_f32 v[194:195], v[186:187], v[144:145], v[194:195]
	v_pk_fma_f32 v[196:197], v[188:189], v[146:147], v[196:197]
	v_pk_fma_f32 v[198:199], v[186:187], v[148:149], v[198:199]
	v_pk_fma_f32 v[200:201], v[188:189], v[150:151], v[200:201]
	v_pk_fma_f32 v[202:203], v[186:187], v[164:165], v[202:203]
	v_pk_fma_f32 v[204:205], v[188:189], v[166:167], v[204:205]
	v_pk_fma_f32 v[206:207], v[186:187], v[168:169], v[206:207]
	v_pk_fma_f32 v[208:209], v[188:189], v[170:171], v[208:209]
	v_add_u32_e32 v235, 0x16000, v232
	s_mov_b64 exec, s[12:13]
	global_store_dwordx4 v235, v[52:55], s[16:17] offset:16
	global_store_dwordx4 v235, v[44:47], s[22:23] offset:16
	global_store_dwordx4 v235, v[194:197], s[20:21] offset:16
	s_mov_b64 exec, s[8:9]
	v_add_u32_e32 v235, 0x5800, v235
	s_mov_b64 exec, s[30:31]
	global_store_dwordx4 v235, v[48:51], s[16:17] offset:16
	global_store_dwordx4 v235, v[4:7], s[22:23] offset:16
	global_store_dwordx4 v235, v[206:209], s[20:21] offset:16
	s_mov_b64 exec, s[8:9]
	v_pk_mul_f32 v[144:145], v[194:195], v[194:195]
	v_pk_mul_f32 v[146:147], v[196:197], v[196:197]
	v_pk_mul_f32 v[148:149], v[198:199], v[198:199]
	v_pk_mul_f32 v[150:151], v[200:201], v[200:201]
	v_pk_mul_f32 v[164:165], v[202:203], v[202:203]
	v_pk_mul_f32 v[166:167], v[204:205], v[204:205]
	v_pk_mul_f32 v[168:169], v[206:207], v[206:207]
	v_pk_mul_f32 v[170:171], v[208:209], v[208:209]
	v_pk_fma_f32 v[144:145], v[144:145], v[174:175], v[172:173]
	v_pk_fma_f32 v[146:147], v[146:147], v[174:175], v[172:173]
	v_pk_fma_f32 v[148:149], v[148:149], v[174:175], v[172:173]
	v_pk_fma_f32 v[150:151], v[150:151], v[174:175], v[172:173]
	v_pk_fma_f32 v[164:165], v[164:165], v[174:175], v[172:173]
	v_pk_fma_f32 v[166:167], v[166:167], v[174:175], v[172:173]
	v_pk_fma_f32 v[168:169], v[168:169], v[174:175], v[172:173]
	v_pk_fma_f32 v[170:171], v[170:171], v[174:175], v[172:173]
	v_pk_mul_f32 v[144:145], v[144:145], v[194:195]
	v_pk_mul_f32 v[146:147], v[146:147], v[196:197]
	v_pk_mul_f32 v[148:149], v[148:149], v[198:199]
	v_pk_mul_f32 v[150:151], v[150:151], v[200:201]
	v_pk_mul_f32 v[164:165], v[164:165], v[202:203]
	v_pk_mul_f32 v[166:167], v[166:167], v[204:205]
	v_pk_mul_f32 v[168:169], v[168:169], v[206:207]
	v_pk_mul_f32 v[170:171], v[170:171], v[208:209]
	v_exp_f32_e32 v144, v144
	v_exp_f32_e32 v146, v146
	v_exp_f32_e32 v148, v148
	v_exp_f32_e32 v150, v150
	v_exp_f32_e32 v164, v164
	v_exp_f32_e32 v166, v166
	v_exp_f32_e32 v168, v168
	v_exp_f32_e32 v170, v170
	v_exp_f32_e32 v145, v145
	v_exp_f32_e32 v147, v147
	v_exp_f32_e32 v149, v149
	v_exp_f32_e32 v151, v151
	v_exp_f32_e32 v165, v165
	v_exp_f32_e32 v167, v167
	v_exp_f32_e32 v169, v169
	v_exp_f32_e32 v171, v171
	v_pk_add_f32 v[144:145], v[144:145], v[210:211]
	v_pk_add_f32 v[146:147], v[146:147], v[210:211]
	v_pk_add_f32 v[148:149], v[148:149], v[210:211]
	v_pk_add_f32 v[150:151], v[150:151], v[210:211]
	v_pk_add_f32 v[164:165], v[164:165], v[210:211]
	v_pk_add_f32 v[166:167], v[166:167], v[210:211]
	v_pk_add_f32 v[168:169], v[168:169], v[210:211]
	v_pk_add_f32 v[170:171], v[170:171], v[210:211]
	v_rcp_f32_e32 v144, v144
	v_rcp_f32_e32 v146, v146
	v_rcp_f32_e32 v148, v148
	v_rcp_f32_e32 v150, v150
	v_rcp_f32_e32 v164, v164
	v_rcp_f32_e32 v166, v166
	v_rcp_f32_e32 v168, v168
	v_rcp_f32_e32 v170, v170
	v_rcp_f32_e32 v145, v145
	v_rcp_f32_e32 v147, v147
	v_rcp_f32_e32 v149, v149
	v_rcp_f32_e32 v151, v151
	v_rcp_f32_e32 v165, v165
	v_rcp_f32_e32 v167, v167
	v_rcp_f32_e32 v169, v169
	v_rcp_f32_e32 v171, v171
	v_pk_mul_f32 v[52:53], v[194:195], v[44:45]
	v_pk_mul_f32 v[54:55], v[196:197], v[46:47]
	v_pk_mul_f32 v[36:37], v[198:199], v[28:29]
	v_pk_mul_f32 v[38:39], v[200:201], v[30:31]
	v_pk_mul_f32 v[32:33], v[202:203], v[24:25]
	v_pk_mul_f32 v[34:35], v[204:205], v[26:27]
	v_pk_mul_f32 v[48:49], v[206:207], v[4:5]
	v_pk_mul_f32 v[50:51], v[208:209], v[6:7]
	v_pk_mul_f32 v[52:53], v[52:53], v[144:145]
	v_pk_mul_f32 v[54:55], v[54:55], v[146:147]
	v_pk_mul_f32 v[36:37], v[36:37], v[148:149]
	v_pk_mul_f32 v[38:39], v[38:39], v[150:151]
	v_pk_mul_f32 v[32:33], v[32:33], v[164:165]
	v_pk_mul_f32 v[34:35], v[34:35], v[166:167]
	v_pk_mul_f32 v[48:49], v[48:49], v[168:169]
	v_pk_mul_f32 v[50:51], v[50:51], v[170:171]
	v_cvt_pk_bf16_f32 v60, v60, v61
	v_cvt_pk_bf16_f32 v61, v62, v63
	v_cvt_pk_bf16_f32 v62, v52, v53
	v_cvt_pk_bf16_f32 v63, v54, v55
	v_cvt_pk_bf16_f32 v20, v20, v21
	v_cvt_pk_bf16_f32 v21, v22, v23
	v_cvt_pk_bf16_f32 v22, v36, v37
	v_cvt_pk_bf16_f32 v23, v38, v39
	v_cvt_pk_bf16_f32 v16, v16, v17
	v_cvt_pk_bf16_f32 v17, v18, v19
	v_cvt_pk_bf16_f32 v18, v32, v33
	v_cvt_pk_bf16_f32 v19, v34, v35
	v_cvt_pk_bf16_f32 v56, v56, v57
	v_cvt_pk_bf16_f32 v57, v58, v59
	v_cvt_pk_bf16_f32 v58, v48, v49
	v_cvt_pk_bf16_f32 v59, v50, v51
	v_add_u32_e32 v235, 0x160000, v233
	s_mov_b64 exec, s[10:11]
	global_store_dwordx4 v235, v[60:63], s[18:19]
	s_mov_b64 exec, s[8:9]
	v_add_u32_e32 v235, 0x18c000, v233
	global_store_dwordx4 v235, v[20:23], s[18:19]
	v_add_u32_e32 v235, 0x1b8000, v233
	global_store_dwordx4 v235, v[16:19], s[18:19]
	v_add_u32_e32 v235, 0x1e4000, v233
	s_mov_b64 exec, s[62:63]
	global_store_dwordx4 v235, v[56:59], s[18:19]
	s_mov_b64 exec, s[8:9]
